# attention unit epilogue rewritten by hand: row-sum reads batched, neighbour-lane exchange by DPP quad_perm instead of one LDS swizzle round trip per element, single exec mask around the 64 stores
# speedup vs baseline: 1.0138x; 1.0138x over previous
; __device__ __forceinline__ unsigned cvt_pk_bf16(float lo, float hi) { const bf16v2_t r = __builtin_convertvector((f32v2_t){lo, hi}, bf16v2_t); return __builtin_bit_cast(unsigned, r); }
; template <int M> __device__ __forceinline__ float swz(float v) { return __int_as_float(__builtin_amdgcn_ds_swizzle(__float_as_int(v), (M << 10) | 0x1F)); }
; __device__ __forceinline__ int crow(int r, int hi) { return (r & 3) + 8 * (r >> 2) + 4 * hi; }
; __device__ __forceinline__ void attn_unit(LAS unsigned char* lds, const bf16_t* __restrict__ Q, const bf16_t* __restrict__ Kg, const bf16_t* __restrict__ Vg, bf16_t* __restrict__ AO, int b, int h, int qb) {
;     ...
;     if (hi == 0) li_l[r32] = l_reg; asm volatile("s_waitcnt lgkmcnt(0)" ::: "memory");
;     bf16_t* Ow = AO + ((size_t)b * SEQ + qlo) * 1024 + h * 128;
; #pragma unroll
;     for (int r = 0; r < 16; ++r) { const int orow = crow(r, hi); const float rl = __builtin_amdgcn_rcpf(li_l[orow]);
; #pragma unroll
;         for (int d0 = 0; d0 < 4; ++d0) { const float v = o[d0][r] * rl; const float vn = swz<1>(v);
;             if ((r32 & 1) == 0) *(unsigned*)(Ow + (size_t)orow * 1024 + d0 * 32 + r32) = cvt_pk_bf16(v, vn); } }
.LBB0_353:
	s_and_saveexec_b64 s[0:1], s[40:41]
	ds_write_b32 v242, v128
	s_or_b64 exec, exec, s[0:1]
	s_waitcnt lgkmcnt(0)
	v_lshl_add_u32 v4, v215, 4, s2
	ds_read_b32 v128, v4
	ds_read_b32 v129, v4 offset:4
	ds_read_b32 v130, v4 offset:8
	ds_read_b32 v131, v4 offset:12
	ds_read_b32 v132, v4 offset:32
	ds_read_b32 v133, v4 offset:36
	ds_read_b32 v134, v4 offset:40
	ds_read_b32 v135, v4 offset:44
	ds_read_b32 v136, v4 offset:64
	ds_read_b32 v137, v4 offset:68
	ds_read_b32 v138, v4 offset:72
	ds_read_b32 v139, v4 offset:76
	ds_read_b32 v140, v4 offset:96
	ds_read_b32 v141, v4 offset:100
	ds_read_b32 v142, v4 offset:104
	ds_read_b32 v143, v4 offset:108
	s_lshl_b32 s0, s30, 11
	s_ashr_i32 s1, s31, 31
	s_add_u32 s0, s31, s0
	s_addc_u32 s1, s1, 0
	s_lshl_b64 s[0:1], s[0:1], 11
	v_readlane_b32 s26, v252, 37
	v_readlane_b32 s27, v252, 38
	s_add_u32 s0, s26, s0
	s_addc_u32 s1, s27, s1
	s_lshl_b32 s3, s3, 8
	s_add_u32 s0, s0, s3
	s_addc_u32 s1, s1, 0
	v_and_b32_e32 v0, 1, v237
	v_lshlrev_b32_e32 v208, 1, v238
	v_cmp_eq_u32_e32 vcc, 0, v0
	v_lshl_add_u64 v[0:1], s[0:1], 0, v[208:209]
	v_lshlrev_b32_e32 v5, 13, v215
	v_readlane_b32 s96, v255, 22
	v_readlane_b32 s97, v255, 23
	v_readlane_b32 s82, v255, 24
	v_readlane_b32 s94, v255, 26
	v_readlane_b32 s88, v255, 27
	s_mov_b32 s65, s35
	s_mov_b32 s89, 0xc000
	s_movk_i32 s95, 0x1ff
	v_readlane_b32 s83, v255, 25
	s_waitcnt lgkmcnt(0)
	v_rcp_f32_e32 v128, v128
	v_rcp_f32_e32 v129, v129
	v_rcp_f32_e32 v130, v130
	v_rcp_f32_e32 v131, v131
	v_rcp_f32_e32 v132, v132
	v_rcp_f32_e32 v133, v133
	v_rcp_f32_e32 v134, v134
	v_rcp_f32_e32 v135, v135
	v_rcp_f32_e32 v136, v136
	v_rcp_f32_e32 v137, v137
	v_rcp_f32_e32 v138, v138
	v_rcp_f32_e32 v139, v139
	v_rcp_f32_e32 v140, v140
	v_rcp_f32_e32 v141, v141
	v_rcp_f32_e32 v142, v142
	v_rcp_f32_e32 v143, v143
	v_mul_f32_e32 v64, v64, v128
	v_mul_f32_e32 v80, v80, v128
	v_mul_f32_e32 v96, v96, v128
	v_mul_f32_e32 v112, v112, v128
	v_mul_f32_e32 v65, v65, v129
	v_mul_f32_e32 v81, v81, v129
	v_mul_f32_e32 v97, v97, v129
	v_mul_f32_e32 v113, v113, v129
	v_mul_f32_e32 v66, v66, v130
	v_mul_f32_e32 v82, v82, v130
	v_mul_f32_e32 v98, v98, v130
	v_mul_f32_e32 v114, v114, v130
	v_mul_f32_e32 v67, v67, v131
	v_mul_f32_e32 v83, v83, v131
	v_mul_f32_e32 v99, v99, v131
	v_mul_f32_e32 v115, v115, v131
	v_mul_f32_e32 v68, v68, v132
	v_mul_f32_e32 v84, v84, v132
	v_mul_f32_e32 v100, v100, v132
	v_mul_f32_e32 v116, v116, v132
	v_mul_f32_e32 v69, v69, v133
	v_mul_f32_e32 v85, v85, v133
	v_mul_f32_e32 v101, v101, v133
	v_mul_f32_e32 v117, v117, v133
	v_mul_f32_e32 v70, v70, v134
	v_mul_f32_e32 v86, v86, v134
	v_mul_f32_e32 v102, v102, v134
	v_mul_f32_e32 v118, v118, v134
	v_mul_f32_e32 v71, v71, v135
	v_mul_f32_e32 v87, v87, v135
	v_mul_f32_e32 v103, v103, v135
	v_mul_f32_e32 v119, v119, v135
	v_mul_f32_e32 v72, v72, v136
	v_mul_f32_e32 v88, v88, v136
	v_mul_f32_e32 v104, v104, v136
	v_mul_f32_e32 v120, v120, v136
	v_mul_f32_e32 v73, v73, v137
	v_mul_f32_e32 v89, v89, v137
	v_mul_f32_e32 v105, v105, v137
	v_mul_f32_e32 v121, v121, v137
	v_mul_f32_e32 v74, v74, v138
	v_mul_f32_e32 v90, v90, v138
	v_mul_f32_e32 v106, v106, v138
	v_mul_f32_e32 v122, v122, v138
	v_mul_f32_e32 v75, v75, v139
	v_mul_f32_e32 v91, v91, v139
	v_mul_f32_e32 v107, v107, v139
	v_mul_f32_e32 v123, v123, v139
	v_mul_f32_e32 v76, v76, v140
	v_mul_f32_e32 v92, v92, v140
	v_mul_f32_e32 v108, v108, v140
	v_mul_f32_e32 v124, v124, v140
	v_mul_f32_e32 v77, v77, v141
	v_mul_f32_e32 v93, v93, v141
	v_mul_f32_e32 v109, v109, v141
	v_mul_f32_e32 v125, v125, v141
	v_mul_f32_e32 v78, v78, v142
	v_mul_f32_e32 v94, v94, v142
	v_mul_f32_e32 v110, v110, v142
	v_mul_f32_e32 v126, v126, v142
	v_mul_f32_e32 v79, v79, v143
	v_mul_f32_e32 v95, v95, v143
	v_mul_f32_e32 v111, v111, v143
	v_mul_f32_e32 v127, v127, v143
	v_mov_b32_dpp v144, v64 quad_perm:[1,0,3,2] row_mask:0xf bank_mask:0xf
	v_mov_b32_dpp v160, v80 quad_perm:[1,0,3,2] row_mask:0xf bank_mask:0xf
	v_mov_b32_dpp v176, v96 quad_perm:[1,0,3,2] row_mask:0xf bank_mask:0xf
	v_mov_b32_dpp v192, v112 quad_perm:[1,0,3,2] row_mask:0xf bank_mask:0xf
	v_mov_b32_dpp v145, v65 quad_perm:[1,0,3,2] row_mask:0xf bank_mask:0xf
	v_mov_b32_dpp v161, v81 quad_perm:[1,0,3,2] row_mask:0xf bank_mask:0xf
	v_mov_b32_dpp v177, v97 quad_perm:[1,0,3,2] row_mask:0xf bank_mask:0xf
	v_mov_b32_dpp v193, v113 quad_perm:[1,0,3,2] row_mask:0xf bank_mask:0xf
	v_mov_b32_dpp v146, v66 quad_perm:[1,0,3,2] row_mask:0xf bank_mask:0xf
	v_mov_b32_dpp v162, v82 quad_perm:[1,0,3,2] row_mask:0xf bank_mask:0xf
	v_mov_b32_dpp v178, v98 quad_perm:[1,0,3,2] row_mask:0xf bank_mask:0xf
	v_mov_b32_dpp v194, v114 quad_perm:[1,0,3,2] row_mask:0xf bank_mask:0xf
	v_mov_b32_dpp v147, v67 quad_perm:[1,0,3,2] row_mask:0xf bank_mask:0xf
	v_mov_b32_dpp v163, v83 quad_perm:[1,0,3,2] row_mask:0xf bank_mask:0xf
	v_mov_b32_dpp v179, v99 quad_perm:[1,0,3,2] row_mask:0xf bank_mask:0xf
	v_mov_b32_dpp v195, v115 quad_perm:[1,0,3,2] row_mask:0xf bank_mask:0xf
	v_mov_b32_dpp v148, v68 quad_perm:[1,0,3,2] row_mask:0xf bank_mask:0xf
	v_mov_b32_dpp v164, v84 quad_perm:[1,0,3,2] row_mask:0xf bank_mask:0xf
	v_mov_b32_dpp v180, v100 quad_perm:[1,0,3,2] row_mask:0xf bank_mask:0xf
	v_mov_b32_dpp v196, v116 quad_perm:[1,0,3,2] row_mask:0xf bank_mask:0xf
	v_mov_b32_dpp v149, v69 quad_perm:[1,0,3,2] row_mask:0xf bank_mask:0xf
	v_mov_b32_dpp v165, v85 quad_perm:[1,0,3,2] row_mask:0xf bank_mask:0xf
	v_mov_b32_dpp v181, v101 quad_perm:[1,0,3,2] row_mask:0xf bank_mask:0xf
	v_mov_b32_dpp v197, v117 quad_perm:[1,0,3,2] row_mask:0xf bank_mask:0xf
	v_mov_b32_dpp v150, v70 quad_perm:[1,0,3,2] row_mask:0xf bank_mask:0xf
	v_mov_b32_dpp v166, v86 quad_perm:[1,0,3,2] row_mask:0xf bank_mask:0xf
; __device__ __forceinline__ unsigned cvt_pk_bf16(float lo, float hi) { const bf16v2_t r = __builtin_convertvector((f32v2_t){lo, hi}, bf16v2_t); return __builtin_bit_cast(unsigned, r); }
; template <int M> __device__ __forceinline__ float swz(float v) { return __int_as_float(__builtin_amdgcn_ds_swizzle(__float_as_int(v), (M << 10) | 0x1F)); }
; __device__ __forceinline__ int crow(int r, int hi) { return (r & 3) + 8 * (r >> 2) + 4 * hi; }
; __device__ __forceinline__ void attn_unit(LAS unsigned char* lds, const bf16_t* __restrict__ Q, const bf16_t* __restrict__ Kg, const bf16_t* __restrict__ Vg, bf16_t* __restrict__ AO, int b, int h, int qb) {
;     ...
;     if (hi == 0) li_l[r32] = l_reg; asm volatile("s_waitcnt lgkmcnt(0)" ::: "memory");
;     bf16_t* Ow = AO + ((size_t)b * SEQ + qlo) * 1024 + h * 128;
; #pragma unroll
;     for (int r = 0; r < 16; ++r) { const int orow = crow(r, hi); const float rl = __builtin_amdgcn_rcpf(li_l[orow]);
; #pragma unroll
;         for (int d0 = 0; d0 < 4; ++d0) { const float v = o[d0][r] * rl; const float vn = swz<1>(v);
;             if ((r32 & 1) == 0) *(unsigned*)(Ow + (size_t)orow * 1024 + d0 * 32 + r32) = cvt_pk_bf16(v, vn); } }
	v_mov_b32_dpp v182, v102 quad_perm:[1,0,3,2] row_mask:0xf bank_mask:0xf
	v_mov_b32_dpp v198, v118 quad_perm:[1,0,3,2] row_mask:0xf bank_mask:0xf
	v_mov_b32_dpp v151, v71 quad_perm:[1,0,3,2] row_mask:0xf bank_mask:0xf
	v_mov_b32_dpp v167, v87 quad_perm:[1,0,3,2] row_mask:0xf bank_mask:0xf
	v_mov_b32_dpp v183, v103 quad_perm:[1,0,3,2] row_mask:0xf bank_mask:0xf
	v_mov_b32_dpp v199, v119 quad_perm:[1,0,3,2] row_mask:0xf bank_mask:0xf
	v_mov_b32_dpp v152, v72 quad_perm:[1,0,3,2] row_mask:0xf bank_mask:0xf
	v_mov_b32_dpp v168, v88 quad_perm:[1,0,3,2] row_mask:0xf bank_mask:0xf
	v_mov_b32_dpp v184, v104 quad_perm:[1,0,3,2] row_mask:0xf bank_mask:0xf
	v_mov_b32_dpp v200, v120 quad_perm:[1,0,3,2] row_mask:0xf bank_mask:0xf
	v_mov_b32_dpp v153, v73 quad_perm:[1,0,3,2] row_mask:0xf bank_mask:0xf
	v_mov_b32_dpp v169, v89 quad_perm:[1,0,3,2] row_mask:0xf bank_mask:0xf
	v_mov_b32_dpp v185, v105 quad_perm:[1,0,3,2] row_mask:0xf bank_mask:0xf
	v_mov_b32_dpp v201, v121 quad_perm:[1,0,3,2] row_mask:0xf bank_mask:0xf
	v_mov_b32_dpp v154, v74 quad_perm:[1,0,3,2] row_mask:0xf bank_mask:0xf
	v_mov_b32_dpp v170, v90 quad_perm:[1,0,3,2] row_mask:0xf bank_mask:0xf
	v_mov_b32_dpp v186, v106 quad_perm:[1,0,3,2] row_mask:0xf bank_mask:0xf
	v_mov_b32_dpp v202, v122 quad_perm:[1,0,3,2] row_mask:0xf bank_mask:0xf
	v_mov_b32_dpp v155, v75 quad_perm:[1,0,3,2] row_mask:0xf bank_mask:0xf
	v_mov_b32_dpp v171, v91 quad_perm:[1,0,3,2] row_mask:0xf bank_mask:0xf
	v_mov_b32_dpp v187, v107 quad_perm:[1,0,3,2] row_mask:0xf bank_mask:0xf
	v_mov_b32_dpp v203, v123 quad_perm:[1,0,3,2] row_mask:0xf bank_mask:0xf
	v_mov_b32_dpp v156, v76 quad_perm:[1,0,3,2] row_mask:0xf bank_mask:0xf
	v_mov_b32_dpp v172, v92 quad_perm:[1,0,3,2] row_mask:0xf bank_mask:0xf
	v_mov_b32_dpp v188, v108 quad_perm:[1,0,3,2] row_mask:0xf bank_mask:0xf
	v_mov_b32_dpp v204, v124 quad_perm:[1,0,3,2] row_mask:0xf bank_mask:0xf
	v_mov_b32_dpp v157, v77 quad_perm:[1,0,3,2] row_mask:0xf bank_mask:0xf
	v_mov_b32_dpp v173, v93 quad_perm:[1,0,3,2] row_mask:0xf bank_mask:0xf
	v_mov_b32_dpp v189, v109 quad_perm:[1,0,3,2] row_mask:0xf bank_mask:0xf
	v_mov_b32_dpp v205, v125 quad_perm:[1,0,3,2] row_mask:0xf bank_mask:0xf
	v_mov_b32_dpp v158, v78 quad_perm:[1,0,3,2] row_mask:0xf bank_mask:0xf
	v_mov_b32_dpp v174, v94 quad_perm:[1,0,3,2] row_mask:0xf bank_mask:0xf
	v_mov_b32_dpp v190, v110 quad_perm:[1,0,3,2] row_mask:0xf bank_mask:0xf
	v_mov_b32_dpp v206, v126 quad_perm:[1,0,3,2] row_mask:0xf bank_mask:0xf
	v_mov_b32_dpp v159, v79 quad_perm:[1,0,3,2] row_mask:0xf bank_mask:0xf
	v_mov_b32_dpp v175, v95 quad_perm:[1,0,3,2] row_mask:0xf bank_mask:0xf
	v_mov_b32_dpp v191, v111 quad_perm:[1,0,3,2] row_mask:0xf bank_mask:0xf
	v_mov_b32_dpp v207, v127 quad_perm:[1,0,3,2] row_mask:0xf bank_mask:0xf
	s_and_saveexec_b64 s[0:1], vcc
	v_mov_b32_e32 v208, v5
	v_lshl_add_u64 v[2:3], v[0:1], 0, v[208:209]
	v_cvt_pk_bf16_f32 v6, v64, v144
	global_store_dword v[2:3], v6, off
	v_cvt_pk_bf16_f32 v7, v80, v160
	global_store_dword v[2:3], v7, off offset:64
	v_cvt_pk_bf16_f32 v8, v96, v176
	global_store_dword v[2:3], v8, off offset:128
	v_cvt_pk_bf16_f32 v9, v112, v192
	global_store_dword v[2:3], v9, off offset:192
	v_or_b32_e32 v208, 0x800, v5
	v_lshl_add_u64 v[2:3], v[0:1], 0, v[208:209]
	v_cvt_pk_bf16_f32 v6, v65, v145
	global_store_dword v[2:3], v6, off
	v_cvt_pk_bf16_f32 v7, v81, v161
	global_store_dword v[2:3], v7, off offset:64
	v_cvt_pk_bf16_f32 v8, v97, v177
	global_store_dword v[2:3], v8, off offset:128
	v_cvt_pk_bf16_f32 v9, v113, v193
	global_store_dword v[2:3], v9, off offset:192
	v_or_b32_e32 v208, 0x1000, v5
	v_lshl_add_u64 v[2:3], v[0:1], 0, v[208:209]
	v_cvt_pk_bf16_f32 v6, v66, v146
	global_store_dword v[2:3], v6, off
	v_cvt_pk_bf16_f32 v7, v82, v162
	global_store_dword v[2:3], v7, off offset:64
	v_cvt_pk_bf16_f32 v8, v98, v178
	global_store_dword v[2:3], v8, off offset:128
	v_cvt_pk_bf16_f32 v9, v114, v194
	global_store_dword v[2:3], v9, off offset:192
	v_or_b32_e32 v208, 0x1800, v5
	v_lshl_add_u64 v[2:3], v[0:1], 0, v[208:209]
	v_cvt_pk_bf16_f32 v6, v67, v147
	global_store_dword v[2:3], v6, off
	v_cvt_pk_bf16_f32 v7, v83, v163
	global_store_dword v[2:3], v7, off offset:64
	v_cvt_pk_bf16_f32 v8, v99, v179
	global_store_dword v[2:3], v8, off offset:128
	v_cvt_pk_bf16_f32 v9, v115, v195
	global_store_dword v[2:3], v9, off offset:192
	v_or_b32_e32 v208, 0x4000, v5
	v_lshl_add_u64 v[2:3], v[0:1], 0, v[208:209]
	v_cvt_pk_bf16_f32 v6, v68, v148
	global_store_dword v[2:3], v6, off
	v_cvt_pk_bf16_f32 v7, v84, v164
; __device__ __forceinline__ unsigned cvt_pk_bf16(float lo, float hi) { const bf16v2_t r = __builtin_convertvector((f32v2_t){lo, hi}, bf16v2_t); return __builtin_bit_cast(unsigned, r); }
; template <int M> __device__ __forceinline__ float swz(float v) { return __int_as_float(__builtin_amdgcn_ds_swizzle(__float_as_int(v), (M << 10) | 0x1F)); }
; __device__ __forceinline__ int crow(int r, int hi) { return (r & 3) + 8 * (r >> 2) + 4 * hi; }
; __device__ __forceinline__ void attn_unit(LAS unsigned char* lds, const bf16_t* __restrict__ Q, const bf16_t* __restrict__ Kg, const bf16_t* __restrict__ Vg, bf16_t* __restrict__ AO, int b, int h, int qb) {
;     ...
;     for (int r = 0; r < 16; ++r) { const int orow = crow(r, hi); const float rl = __builtin_amdgcn_rcpf(li_l[orow]);
; #pragma unroll
;         for (int d0 = 0; d0 < 4; ++d0) { const float v = o[d0][r] * rl; const float vn = swz<1>(v);
;             if ((r32 & 1) == 0) *(unsigned*)(Ow + (size_t)orow * 1024 + d0 * 32 + r32) = cvt_pk_bf16(v, vn); } }
	global_store_dword v[2:3], v7, off offset:64
	v_cvt_pk_bf16_f32 v8, v100, v180
	global_store_dword v[2:3], v8, off offset:128
	v_cvt_pk_bf16_f32 v9, v116, v196
	global_store_dword v[2:3], v9, off offset:192
	v_or_b32_e32 v208, 0x4800, v5
	v_lshl_add_u64 v[2:3], v[0:1], 0, v[208:209]
	v_cvt_pk_bf16_f32 v6, v69, v149
	global_store_dword v[2:3], v6, off
	v_cvt_pk_bf16_f32 v7, v85, v165
	global_store_dword v[2:3], v7, off offset:64
	v_cvt_pk_bf16_f32 v8, v101, v181
	global_store_dword v[2:3], v8, off offset:128
	v_cvt_pk_bf16_f32 v9, v117, v197
	global_store_dword v[2:3], v9, off offset:192
	v_or_b32_e32 v208, 0x5000, v5
	v_lshl_add_u64 v[2:3], v[0:1], 0, v[208:209]
	v_cvt_pk_bf16_f32 v6, v70, v150
	global_store_dword v[2:3], v6, off
	v_cvt_pk_bf16_f32 v7, v86, v166
	global_store_dword v[2:3], v7, off offset:64
	v_cvt_pk_bf16_f32 v8, v102, v182
	global_store_dword v[2:3], v8, off offset:128
	v_cvt_pk_bf16_f32 v9, v118, v198
	global_store_dword v[2:3], v9, off offset:192
	v_or_b32_e32 v208, 0x5800, v5
	v_lshl_add_u64 v[2:3], v[0:1], 0, v[208:209]
	v_cvt_pk_bf16_f32 v6, v71, v151
	global_store_dword v[2:3], v6, off
	v_cvt_pk_bf16_f32 v7, v87, v167
	global_store_dword v[2:3], v7, off offset:64
	v_cvt_pk_bf16_f32 v8, v103, v183
	global_store_dword v[2:3], v8, off offset:128
	v_cvt_pk_bf16_f32 v9, v119, v199
	global_store_dword v[2:3], v9, off offset:192
	v_or_b32_e32 v208, 0x8000, v5
	v_lshl_add_u64 v[2:3], v[0:1], 0, v[208:209]
	v_cvt_pk_bf16_f32 v6, v72, v152
	global_store_dword v[2:3], v6, off
	v_cvt_pk_bf16_f32 v7, v88, v168
	global_store_dword v[2:3], v7, off offset:64
	v_cvt_pk_bf16_f32 v8, v104, v184
	global_store_dword v[2:3], v8, off offset:128
	v_cvt_pk_bf16_f32 v9, v120, v200
	global_store_dword v[2:3], v9, off offset:192
	v_or_b32_e32 v208, 0x8800, v5
	v_lshl_add_u64 v[2:3], v[0:1], 0, v[208:209]
	v_cvt_pk_bf16_f32 v6, v73, v153
	global_store_dword v[2:3], v6, off
	v_cvt_pk_bf16_f32 v7, v89, v169
	global_store_dword v[2:3], v7, off offset:64
	v_cvt_pk_bf16_f32 v8, v105, v185
	global_store_dword v[2:3], v8, off offset:128
	v_cvt_pk_bf16_f32 v9, v121, v201
	global_store_dword v[2:3], v9, off offset:192
	v_or_b32_e32 v208, 0x9000, v5
	v_lshl_add_u64 v[2:3], v[0:1], 0, v[208:209]
	v_cvt_pk_bf16_f32 v6, v74, v154
	global_store_dword v[2:3], v6, off
	v_cvt_pk_bf16_f32 v7, v90, v170
	global_store_dword v[2:3], v7, off offset:64
	v_cvt_pk_bf16_f32 v8, v106, v186
	global_store_dword v[2:3], v8, off offset:128
	v_cvt_pk_bf16_f32 v9, v122, v202
	global_store_dword v[2:3], v9, off offset:192
	v_or_b32_e32 v208, 0x9800, v5
	v_lshl_add_u64 v[2:3], v[0:1], 0, v[208:209]
	v_cvt_pk_bf16_f32 v6, v75, v155
	global_store_dword v[2:3], v6, off
	v_cvt_pk_bf16_f32 v7, v91, v171
	global_store_dword v[2:3], v7, off offset:64
	v_cvt_pk_bf16_f32 v8, v107, v187
	global_store_dword v[2:3], v8, off offset:128
	v_cvt_pk_bf16_f32 v9, v123, v203
	global_store_dword v[2:3], v9, off offset:192
	v_or_b32_e32 v208, 0xc000, v5
	v_lshl_add_u64 v[2:3], v[0:1], 0, v[208:209]
	v_cvt_pk_bf16_f32 v6, v76, v156
	global_store_dword v[2:3], v6, off
	v_cvt_pk_bf16_f32 v7, v92, v172
	global_store_dword v[2:3], v7, off offset:64
	v_cvt_pk_bf16_f32 v8, v108, v188
	global_store_dword v[2:3], v8, off offset:128
	v_cvt_pk_bf16_f32 v9, v124, v204
	global_store_dword v[2:3], v9, off offset:192
	v_or_b32_e32 v208, 0xc800, v5
	v_lshl_add_u64 v[2:3], v[0:1], 0, v[208:209]
	v_cvt_pk_bf16_f32 v6, v77, v157
	global_store_dword v[2:3], v6, off
	v_cvt_pk_bf16_f32 v7, v93, v173
	global_store_dword v[2:3], v7, off offset:64
	v_cvt_pk_bf16_f32 v8, v109, v189
	global_store_dword v[2:3], v8, off offset:128
	v_cvt_pk_bf16_f32 v9, v125, v205
	global_store_dword v[2:3], v9, off offset:192
	v_or_b32_e32 v208, 0xd000, v5
	v_lshl_add_u64 v[2:3], v[0:1], 0, v[208:209]
	v_cvt_pk_bf16_f32 v6, v78, v158
	global_store_dword v[2:3], v6, off
	v_cvt_pk_bf16_f32 v7, v94, v174
	global_store_dword v[2:3], v7, off offset:64
	v_cvt_pk_bf16_f32 v8, v110, v190
	global_store_dword v[2:3], v8, off offset:128
	v_cvt_pk_bf16_f32 v9, v126, v206
	global_store_dword v[2:3], v9, off offset:192
	v_or_b32_e32 v208, 0xd800, v5
	v_lshl_add_u64 v[2:3], v[0:1], 0, v[208:209]
	v_cvt_pk_bf16_f32 v6, v79, v159
	global_store_dword v[2:3], v6, off
	v_cvt_pk_bf16_f32 v7, v95, v175
	global_store_dword v[2:3], v7, off offset:64
	v_cvt_pk_bf16_f32 v8, v111, v191
	global_store_dword v[2:3], v8, off offset:128
	v_cvt_pk_bf16_f32 v9, v127, v207
	global_store_dword v[2:3], v9, off offset:192
	s_branch .LBB0_293
